# mamba scan: next sample unit state (32 KB) prefetched one unit ahead into spare VGPRs
# baseline (speedup 1.0000x reference)
; __device__ __forceinline__ int TID() { int t = threadIdx.x; asm volatile("" : "+v"(t)); return t; }
; __device__ __forceinline__ int BID() { int t = blockIdx.x; asm volatile("" : "+s"(t)); return t; }
; __device__ __forceinline__ void mamba_block(ArgsP a_, unsigned char* smem) { const ArgsP a = a_;
;     ...
;     const int tid = TID(), wid = tid >> 6, lane = tid & 63, fr = lane & 15, fq = lane >> 4;
;     const int G = gridDim.x, cb0 = BID();
;     const int cb = (G == 256) ? ((((cb0 & 7) * 8 + (cb0 >> 5)) << 2) | ((cb0 >> 3) & 3)) : cb0;
;     const unsigned char* proj = a->ws + B_PROJ;
;     const bf16_t* ZG = (const bf16_t*)proj; const float* DT = (const float*)(proj + (size_t)MP * 12288); const bf16_t* XC = (const bf16_t*)(proj + (size_t)MP * 13312);
;     bf16_t* YB = (bf16_t*)(a->ws + B_PART);
;     const int np = cb < 256 ? 33 : 0; const int nsmp = (4096 - (cb % 256) + G - 1) / G; const int nunits = np + nsmp;
;     f32x4 S[1][4]; f32x4 O[2];
;     u32x4 bpre[2], cpre[2]; bf16_t xpre[8]; float dtpre = 0.f;
;     const int vv = tid & 63, jg = tid >> 6;
;     ...
;     if (nunits > 0) MB_LOAD(0);
;     const int ntot_ = np + nsmp * REP_SMP;
.LBB0_322:
	s_add_u32 s24, s26, 0x208e0000
	s_addc_u32 s25, s27, 0
	s_add_u32 s26, s26, 0x17ee0000
	s_addc_u32 s27, s27, 0
	s_ashr_i32 s22, s18, 5
	v_lshrrev_b32_e32 v22, 4, v18
	v_writelane_b32 v255, s22, 14
	s_mulk_i32 s22, 0x810
	v_writelane_b32 v255, s22, 4
	v_lshlrev_b32_e32 v23, 4, v19
	v_lshlrev_b32_e32 v24, 2, v22
	v_lshlrev_b32_e32 v25, 2, v57
	s_add_i32 s22, 0, 0x18000
	v_readlane_b32 s64, v254, 33
	v_readlane_b32 s66, v254, 34
	v_or_b32_e32 v20, v24, v23
	v_lshlrev_b32_e32 v16, 4, v57
	v_add_u32_e32 v69, s22, v25
	v_add_u32_e32 v76, s64, v25
	v_add_u32_e32 v77, s66, v25
	v_mul_u32_u24_e32 v25, 0x48, v18
	v_readlane_b32 s34, v255, 12
	v_ashrrev_i32_e32 v21, 31, v20
	v_and_b32_e32 v16, 0xf0, v16
	v_lshl_add_u32 v25, v25, 1, 0
	s_movk_i32 s23, 0xff74
	v_readlane_b32 s35, v255, 13
	v_lshlrev_b64 v[58:59], 8, v[20:21]
	v_add_u32_e32 v20, 0, v16
	v_add_u32_e32 v79, v25, v23
	v_mad_i32_i24 v25, v18, s23, v25
	v_mul_u32_u24_e32 v26, 0x11c, v18
	v_lshl_add_u64 v[60:61], s[34:35], 0, v[16:17]
	v_lshlrev_b32_e32 v16, 1, v18
	v_add3_u32 v80, v25, v26, v23
	v_lshl_add_u64 v[62:63], s[34:35], 0, v[16:17]
	v_lshlrev_b32_e32 v26, 5, v19
	v_lshlrev_b32_e32 v16, 3, v22
	v_readlane_b32 s23, v254, 35
	v_lshlrev_b32_e32 v29, 1, v19
	v_and_b32_e32 v56, 15, v57
	v_add3_u32 v22, s23, v26, v16
	v_ashrrev_i32_e32 v16, 7, v57
	v_and_b32_e32 v29, 2, v29
	v_and_b32_e32 v30, 48, v18
	v_lshl_or_b32 v28, v16, 4, v56
	v_cmp_le_i32_e64 s[42:43], v29, v16
	v_cmp_ge_i32_e64 s[44:45], v29, v16
	v_add_u32_e32 v16, 0, v30
	s_movk_i32 s67, 0x110
	v_mad_u64_u32 v[64:65], s[34:35], v28, s67, v[16:17]
	v_add_u32_e32 v31, s23, v30
	s_movk_i32 s23, 0x90
	v_lshlrev_b32_e32 v32, 4, v29
	v_mul_lo_u32 v35, v28, s23
	v_readlane_b32 s34, v254, 36
	v_or_b32_e32 v23, v23, v56
	v_lshlrev_b32_e32 v21, 3, v57
	v_or_b32_e32 v33, v32, v56
	v_add_u32_e32 v35, s34, v35
	v_or_b32_e32 v66, v32, v24
	v_mad_u64_u32 v[70:71], s[34:35], v23, s23, v[16:17]
	v_ashrrev_i32_e32 v32, 3, v57
	v_ashrrev_i32_e32 v85, 4, v57
	v_lshlrev_b32_e32 v78, 3, v19
	v_bfi_b32 v71, -16, v32, v57
	v_mad_u64_u32 v[72:73], s[34:35], v85, s67, v[20:21]
	v_add_u32_e32 v32, 0x200, v57
	v_or_b32_e32 v24, 2, v66
	v_ashrrev_i32_e32 v73, 4, v32
	v_or_b32_e32 v88, 2, v78
	v_cmp_gt_i32_e64 s[50:51], v24, v28
	v_or_b32_e32 v24, 3, v66
	v_mad_u64_u32 v[74:75], s[34:35], v73, s67, v[20:21]
	v_lshlrev_b32_e32 v20, 2, v88
	v_or_b32_e32 v92, 4, v78
	v_lshlrev_b32_e32 v29, 6, v29
	v_cmp_gt_i32_e64 s[52:53], v24, v28
	v_or_b32_e32 v24, 18, v66
	v_add_u32_e32 v89, s64, v20
	v_add_u32_e32 v91, s66, v20
	v_lshlrev_b32_e32 v20, 2, v92
	v_or_b32_e32 v96, 6, v78
	v_lshl_add_u32 v81, v28, 2, s22
	v_add3_u32 v82, s22, v30, v29
	v_or_b32_e32 v68, 16, v66
	v_cmp_gt_i32_e64 s[58:59], v24, v28
	v_or_b32_e32 v24, 19, v66
	v_add_u32_e32 v84, v35, v30
	v_readlane_b32 s22, v254, 37
	v_mov_b32_e32 v30, 0x1200
	v_add_u32_e32 v93, s64, v20
	v_add_u32_e32 v95, s66, v20
	v_lshlrev_b32_e32 v20, 2, v96
	s_abs_i32 s65, s65
	v_cmp_gt_i32_e64 s[46:47], v66, v28
	v_cmp_lt_i32_e64 s[48:49], v66, v28
	v_cmp_gt_i32_e64 s[54:55], v68, v28
	v_cmp_lt_i32_e64 s[56:57], v68, v28
	v_cmp_gt_i32_e64 s[60:61], v24, v28
	v_lshl_add_u32 v28, v19, 6, s22
	v_mad_u32_u24 v30, v56, s23, v30
	v_cmp_eq_u32_e64 s[22:23], 0, v18
	v_add_u32_e32 v97, s64, v20
	v_add_u32_e32 v99, s66, v20
	v_cvt_f32_u32_e32 v20, s65
	v_writelane_b32 v255, s22, 16
	v_add_u32_e32 v75, s64, v26
	v_add_u32_e32 v87, s66, v26
	v_writelane_b32 v255, s23, 17
	v_cmp_gt_u32_e64 s[22:23], 2, v18
	v_rcp_iflag_f32_e32 v20, v20
	v_mul_u32_u24_e32 v27, 0x110, v56
	v_writelane_b32 v255, s22, 18
	v_mul_u32_u24_e32 v34, 0x110, v33
	v_mul_f32_e32 v20, 0x4f7ffffe, v20
	v_writelane_b32 v255, s23, 19
	v_cmp_gt_u32_e64 s[22:23], 4, v18
	v_cvt_u32_f32_e32 v20, v20
	v_mul_u32_u24_e32 v24, 0x90, v33
	v_writelane_b32 v255, s22, 20
	v_and_b32_e32 v29, 48, v57
	v_mul_u32_u24_e32 v23, 0x90, v56
	v_writelane_b32 v255, s23, 21
	v_cmp_gt_u32_e64 s[22:23], 8, v18
	v_cmp_gt_i32_e64 s[40:41], 64, v57
	v_mad_u32_u24 v65, v33, s67, v16
	v_writelane_b32 v255, s22, 22
	v_lshl_add_u32 v83, v66, 1, v35
	s_mov_b32 s34, 0
	v_writelane_b32 v255, s23, 23
	v_cmp_gt_u32_e64 s[22:23], 16, v18
	v_or_b32_e32 v86, 1, v78
	v_or_b32_e32 v90, 3, v78
	v_writelane_b32 v255, s22, 24
	v_or_b32_e32 v94, 5, v78
	v_or_b32_e32 v98, 7, v78
	v_writelane_b32 v255, s23, 25
	v_cmp_gt_u32_e64 s[22:23], 32, v18
	v_lshlrev_b32_e32 v18, 2, v18
	v_add_u32_e32 v109, v22, v27
	v_writelane_b32 v255, s22, 26
	v_add_u32_e32 v110, v16, v24
	v_add_u32_e32 v111, v28, v29
	v_writelane_b32 v255, s23, 27
	s_movk_i32 s22, 0x880
	v_mul_lo_u32 v19, v19, s22
	s_sub_i32 s22, 0, s65
	v_readfirstlane_b32 s23, v20
	v_add_u32_e32 v100, v25, v19
	v_add3_u32 v101, 0, v19, v18
	v_mul_lo_u32 v19, v88, s67
	s_mul_i32 s22, s22, s23
	v_add_u32_e32 v102, v25, v19
	v_add3_u32 v103, 0, v19, v18
	v_add_u32_e32 v26, 0x220, v19
	v_add_u32_e32 v19, 0x440, v19
	s_mul_hi_u32 s22, s23, s22
	v_add3_u32 v105, 0, v26, v18
	v_add3_u32 v107, 0, v19, v18
	s_add_i32 s66, s23, s22
	s_sub_i32 s22, s68, s69
	v_mov_b32_e32 v20, 0
	v_add_u32_e32 v18, 0, v21
	v_add_u32_e32 v104, v25, v26
	v_add_u32_e32 v106, v25, v19
	s_sub_i32 s67, 0, s19
	s_sub_i32 s68, s22, s19
	v_add_u32_e32 v108, 0x18100, v18
	v_add_u32_e32 v112, v16, v23
	v_add_u32_e32 v113, v16, v30
	v_add_u32_e32 v114, v31, v34
	v_mov_b32_e32 v21, v20
	v_mov_b32_e32 v22, v20
	v_mov_b32_e32 v23, v20
	v_mov_b32_e32 v24, v20
	v_mov_b32_e32 v25, v20
	v_mov_b32_e32 v26, v20
	v_mov_b32_e32 v27, v20
	v_mov_b32_e32 v28, v20
	v_mov_b32_e32 v29, v20
	v_mov_b32_e32 v30, v20
	v_mov_b32_e32 v31, v20
	v_mov_b32_e32 v32, v20
	v_mov_b32_e32 v33, v20
	v_mov_b32_e32 v34, v20
	v_mov_b32_e32 v35, v20
	s_mov_b32 s22, 0
	s_nop 0
	v_writelane_b32 v255, s22, 42
	s_branch .LBB0_324

; template <int DK, int DV>
; __device__ __forceinline__ void state_load(f32x4 (&S)[DK / 128][DV / 16], const float* src, int ldv, int wid, int fr, int fq, bool zero) {
; #pragma unroll
;     for (int ct = 0; ct < DK / 128; ++ct)
; #pragma unroll
;         for (int vt = 0; vt < DV / 16; ++vt) {
;             if (zero) S[ct][vt] = (f32x4){0.f, 0.f, 0.f, 0.f};
;             else { const float* p = src + (size_t)(16 * (wid * (DK / 128) + ct) + 4 * fq) * ldv + 16 * vt + fr; S[ct][vt] = (f32x4){p[0], p[ldv], p[2 * ldv], p[3 * ldv]}; }
;         }
; __device__ __forceinline__ void mamba_block(ArgsP a_, unsigned char* smem) { const ArgsP a = a_;
;     ...
;         if (first) state_load<128, 64>(S, AIN(4) + (((size_t)b * 32 + hd) * 128) * 64, 64, wid, fr, fq, !sample);
.LBB0_336:
	v_lshl_add_u64 v[18:19], s[76:77], 0, v[58:59]
	v_lshlrev_b32_e32 v16, 2, v56
	v_mov_b32_e32 v20, 0
	v_lshl_add_u64 v[18:19], v[18:19], 0, v[16:17]
	s_andn2_b64 vcc, exec, s[78:79]
	v_mov_b32_e32 v21, v20
	v_mov_b32_e32 v22, v20
	v_mov_b32_e32 v23, v20
	v_mov_b32_e32 v24, v20
	v_mov_b32_e32 v25, v20
	v_mov_b32_e32 v26, v20
	v_mov_b32_e32 v27, v20
	s_cbranch_vccnz .LBB0_338
	v_readlane_b32 s22, v255, 42
	s_nop 1
	s_cmp_eq_u32 s22, 0
	s_cbranch_scc1 .Lmb_sld_a
	v_mov_b32_e32 v20, v130
	v_mov_b32_e32 v21, v131
	v_mov_b32_e32 v22, v132
	v_mov_b32_e32 v23, v133
	v_mov_b32_e32 v27, v137
	v_mov_b32_e32 v26, v136
	v_mov_b32_e32 v25, v135
	v_mov_b32_e32 v24, v134
	s_branch .LBB0_338
.Lmb_sld_a:
	global_load_dword v20, v[18:19], off
	global_load_dword v21, v[18:19], off offset:256
	global_load_dword v22, v[18:19], off offset:512
	global_load_dword v23, v[18:19], off offset:768
	global_load_dword v27, v[18:19], off offset:832
	global_load_dword v26, v[18:19], off offset:576
	global_load_dword v25, v[18:19], off offset:320
	global_load_dword v24, v[18:19], off offset:64

; template <int DK, int DV>
; __device__ __forceinline__ void state_load(f32x4 (&S)[DK / 128][DV / 16], const float* src, int ldv, int wid, int fr, int fq, bool zero) {
; #pragma unroll
;     for (int ct = 0; ct < DK / 128; ++ct)
; #pragma unroll
;         for (int vt = 0; vt < DV / 16; ++vt) {
;             if (zero) S[ct][vt] = (f32x4){0.f, 0.f, 0.f, 0.f};
;             else { const float* p = src + (size_t)(16 * (wid * (DK / 128) + ct) + 4 * fq) * ldv + 16 * vt + fr; S[ct][vt] = (f32x4){p[0], p[ldv], p[2 * ldv], p[3 * ldv]}; }
;         }
; __device__ __forceinline__ void mamba_block(ArgsP a_, unsigned char* smem) { const ArgsP a = a_;
;     ...
;         if (first) state_load<128, 64>(S, AIN(4) + (((size_t)b * 32 + hd) * 128) * 64, 64, wid, fr, fq, !sample);
.LBB0_340:
	v_mov_b32_e32 v28, 0
	s_andn2_b64 vcc, exec, s[76:77]
	v_mov_b32_e32 v29, 0
	v_mov_b32_e32 v30, 0
	v_mov_b32_e32 v31, 0
	v_mov_b32_e32 v32, 0
	v_mov_b32_e32 v33, 0
	v_mov_b32_e32 v34, 0
	v_mov_b32_e32 v35, 0
	s_cbranch_vccnz .LBB0_342
	v_readlane_b32 s22, v255, 42
	s_nop 1
	s_cmp_eq_u32 s22, 0
	s_cbranch_scc1 .Lmb_sld_b
	v_mov_b32_e32 v28, v138
	v_mov_b32_e32 v29, v139
	v_mov_b32_e32 v30, v140
	v_mov_b32_e32 v31, v141
	v_mov_b32_e32 v35, v145
	v_mov_b32_e32 v34, v144
	v_mov_b32_e32 v33, v143
	v_mov_b32_e32 v32, v142
	s_mov_b32 s22, 0
	s_nop 0
	v_writelane_b32 v255, s22, 42
	s_branch .LBB0_342
.Lmb_sld_b:
	global_load_dword v28, v[18:19], off offset:128
	global_load_dword v29, v[18:19], off offset:384
	global_load_dword v30, v[18:19], off offset:640
	global_load_dword v31, v[18:19], off offset:896
	global_load_dword v35, v[18:19], off offset:960
	global_load_dword v34, v[18:19], off offset:704
	global_load_dword v33, v[18:19], off offset:448
	global_load_dword v32, v[18:19], off offset:192

; __device__ __forceinline__ unsigned cvt_pk_bf16(float lo, float hi) { unsigned r; asm("v_cvt_pk_bf16_f32 %0, %1, %2" : "=v"(r) : "v"(lo), "v"(hi)); return r; }
; template <int DK, int DV, bool SEPQ> ...
;     ...
;         for (int ks = 0; ks < DK / 32; ++ks) {
;             const bf16x8 qf = *(const bf16x8*)(QA + (16 * m + fr) * LQ + 32 * ks + 8 * fq);
;             if (do0) { const bf16x8 kf = *(const bf16x8*)(KB + (16 * n0 + fr) * LQ + 32 * ks + 8 * fq); acc0 = __builtin_amdgcn_mfma_f32_16x16x32_bf16(kf, qf, acc0, 0, 0, 0); }
;             if (do1) { const bf16x8 kf = *(const bf16x8*)(KB + (16 * n1 + fr) * LQ + 32 * ks + 8 * fq); acc1 = __builtin_amdgcn_mfma_f32_16x16x32_bf16(kf, qf, acc1, 0, 0, 0); }
;             bf16x8 qs = qf; if (SEPQ) qs = *(const bf16x8*)(QS + (16 * m + fr) * LQ + 32 * ks + 8 * fq);
; #pragma unroll
;             for (int vt = 0; vt < NVTW; ++vt) { const bf16x8 sf = *(const bf16x8*)(ST + (16 * (hw * NVTW + vt) + fr) * LQ + 32 * ks + 8 * fq); O[vt] = __builtin_amdgcn_mfma_f32_16x16x32_bf16(sf, qs, O[vt], 0, 0, 0); }
;         }
; #pragma unroll
;         for (int nn = 0; nn < 2; ++nn) {
;             const int n = 2 * hw + nn; const f32x4 acc = nn == 0 ? acc0 : acc1;
;             const f32x4 gj = *(const f32x4*)(GI + 16 * n + 4 * fq); const int i = 16 * m + fr, j0 = 16 * n + 4 * fq; float p[4];
; #pragma unroll
;             for (int e = 0; e < 4; ++e) p[e] = (j0 + e <= i) ? acc[e] * __expf(gi_i - gj[e]) : 0.f;
;             u32x2 w; w.x = cvt_pk_bf16(p[0], p[1]); w.y = cvt_pk_bf16(p[2], p[3]); *(u32x2*)(P + (16 * m + fr) * LJ + j0) = w;
;         }
;         const float ei = __expf(gi_i);
; #pragma unroll
;         for (int vt = 0; vt < NVTW; ++vt) O[vt] = O[vt] * ei;
;     }
;     __syncthreads();
.LBB0_355:
	s_or_b64 exec, exec, s[96:97]
	v_readlane_b32 s93, v254, 53
	s_cmp_ge_i32 s80, s19
	s_cbranch_scc0 .Lmb_spf_skip
	s_load_dwordx2 s[76:77], s[4:5], 0x20
	s_sub_i32 s22, s80, s19
	s_mul_i32 s22, s22, s13
	s_add_i32 s22, s22, s62
	s_ashr_i32 s23, s22, 31
	s_lshl_b64 s[22:23], s[22:23], 15
	s_waitcnt lgkmcnt(0)
	s_add_u32 s76, s76, s22
	s_addc_u32 s77, s77, s23
	v_lshl_add_u64 v[126:127], s[76:77], 0, v[58:59]
	v_lshlrev_b32_e32 v184, 2, v56
	v_mov_b32_e32 v185, 0
	v_lshl_add_u64 v[126:127], v[126:127], 0, v[184:185]
	global_load_dword v130, v[126:127], off
	global_load_dword v131, v[126:127], off offset:256
	global_load_dword v132, v[126:127], off offset:512
	global_load_dword v133, v[126:127], off offset:768
	global_load_dword v134, v[126:127], off offset:64
	global_load_dword v135, v[126:127], off offset:320
	global_load_dword v136, v[126:127], off offset:576
	global_load_dword v137, v[126:127], off offset:832
	global_load_dword v138, v[126:127], off offset:128
	global_load_dword v139, v[126:127], off offset:384
	global_load_dword v140, v[126:127], off offset:640
	global_load_dword v141, v[126:127], off offset:896
	global_load_dword v142, v[126:127], off offset:192
	global_load_dword v143, v[126:127], off offset:448
	global_load_dword v144, v[126:127], off offset:704
	global_load_dword v145, v[126:127], off offset:960
	s_mov_b32 s22, 1
	s_nop 0
	v_writelane_b32 v255, s22, 42
.Lmb_spf_skip:
.LBB0_356:
	s_load_dwordx2 s[22:23], s[4:5], 0xc0
	v_add_u32_e32 v212, s72, v71
	v_ashrrev_i32_e32 v213, 31, v212
	v_lshlrev_b64 v[214:215], 11, v[212:213]
	v_lshlrev_b64 v[212:213], 13, v[212:213]
	v_readlane_b32 s74, v255, 12
	v_readlane_b32 s75, v255, 13
	v_lshl_or_b32 v216, s71, 6, v214
	v_or_b32_e32 v214, v216, v66
	s_nop 0
	v_lshl_add_u64 v[212:213], s[74:75], 0, v[212:213]
	s_lshl_b32 s74, s71, 7
	s_mov_b32 s75, s12
	v_lshl_add_u64 v[212:213], v[212:213], 0, s[74:75]
	v_lshlrev_b32_e32 v218, 1, v66
	v_mov_b32_e32 v219, 0
	v_lshl_add_u64 v[212:213], v[212:213], 0, v[218:219]
	v_lshlrev_b64 v[218:219], 1, v[214:215]
	global_load_dwordx2 v[202:203], v[212:213], off
	v_lshl_add_u64 v[218:219], s[24:25], 0, v[218:219]
	global_load_dwordx2 v[204:205], v[218:219], off
	global_load_dwordx2 v[206:207], v[212:213], off offset:32
	v_or_b32_e32 v214, v216, v68
	v_lshlrev_b64 v[218:219], 1, v[214:215]
	v_lshl_add_u64 v[218:219], s[24:25], 0, v[218:219]
	global_load_dwordx2 v[208:209], v[218:219], off
	s_lshl_b32 s74, s71, 2
	v_mov_b32_e32 v217, s74
	s_waitcnt lgkmcnt(0)
	global_load_dword v210, v217, s[22:23]
	s_waitcnt lgkmcnt(0)
	ds_read_b32 v123, v81
	ds_read_b128 v[220:223], v64
	ds_read_b128 v[224:227], v65 offset:17408
	ds_read_b128 v[228:231], v65 offset:21760
	ds_read_b128 v[232:235], v114
	ds_read_b128 v[236:239], v114 offset:4352
	ds_read_b128 v[164:167], v64 offset:64
	ds_read_b128 v[168:171], v65 offset:17472
	ds_read_b128 v[172:175], v65 offset:21824
	ds_read_b128 v[176:179], v114 offset:64
	ds_read_b128 v[180:183], v114 offset:4416
	s_waitcnt lgkmcnt(5)
	v_mfma_f32_16x16x32_bf16 v[40:43], v[224:227], v[220:223], 0
	v_mfma_f32_16x16x32_bf16 v[36:39], v[228:231], v[220:223], 0
	v_mfma_f32_16x16x32_bf16 v[44:47], v[232:235], v[220:223], 0
	v_mfma_f32_16x16x32_bf16 v[48:51], v[236:239], v[220:223], 0
	ds_read_b128 v[220:223], v64 offset:128
	ds_read_b128 v[224:227], v65 offset:17536
	ds_read_b128 v[228:231], v65 offset:21888
	ds_read_b128 v[232:235], v114 offset:128
	ds_read_b128 v[236:239], v114 offset:4480
	s_waitcnt lgkmcnt(5)
	v_mfma_f32_16x16x32_bf16 v[40:43], v[168:171], v[164:167], v[40:43]
	v_mfma_f32_16x16x32_bf16 v[36:39], v[172:175], v[164:167], v[36:39]
	v_mfma_f32_16x16x32_bf16 v[44:47], v[176:179], v[164:167], v[44:47]
	v_mfma_f32_16x16x32_bf16 v[48:51], v[180:183], v[164:167], v[48:51]
	ds_read_b128 v[164:167], v64 offset:192
	ds_read_b128 v[168:171], v65 offset:17600
	ds_read_b128 v[172:175], v65 offset:21952
	ds_read_b128 v[176:179], v114 offset:192
	ds_read_b128 v[180:183], v114 offset:4544
	s_waitcnt lgkmcnt(5)
	v_mfma_f32_16x16x32_bf16 v[40:43], v[224:227], v[220:223], v[40:43]
	v_mfma_f32_16x16x32_bf16 v[36:39], v[228:231], v[220:223], v[36:39]
	v_mfma_f32_16x16x32_bf16 v[44:47], v[232:235], v[220:223], v[44:47]
	v_mfma_f32_16x16x32_bf16 v[48:51], v[236:239], v[220:223], v[48:51]
	s_waitcnt lgkmcnt(0)
	v_mfma_f32_16x16x32_bf16 v[40:43], v[168:171], v[164:167], v[40:43]
	v_mfma_f32_16x16x32_bf16 v[36:39], v[172:175], v[164:167], v[36:39]
	v_mfma_f32_16x16x32_bf16 v[44:47], v[176:179], v[164:167], v[44:47]
	v_mfma_f32_16x16x32_bf16 v[48:51], v[180:183], v[164:167], v[48:51]
	s_nop 7
	v_cmp_gt_i32_e32 vcc, s73, v71
	ds_read_b128 v[52:55], v82
	s_waitcnt lgkmcnt(0)
	v_sub_f32_e32 v16, v123, v52
	v_mul_f32_e32 v16, 0x3fb8aa3b, v16
	v_exp_f32_e32 v16, v16
	v_sub_f32_e32 v18, v123, v53
	v_sub_f32_e32 v19, v123, v54
	v_mul_f32_e32 v18, 0x3fb8aa3b, v18
	v_mul_f32_e32 v16, v40, v16
	v_mul_f32_e32 v19, 0x3fb8aa3b, v19
	v_sub_f32_e32 v40, v123, v55
	v_exp_f32_e32 v18, v18
	v_exp_f32_e32 v19, v19
	v_mul_f32_e32 v40, 0x3fb8aa3b, v40
	v_exp_f32_e32 v40, v40
	v_mul_f32_e32 v18, v41, v18
	v_mul_f32_e32 v19, v42, v19
	v_cndmask_b32_e64 v18, 0, v18, s[48:49]
	v_cndmask_b32_e64 v19, v19, 0, s[50:51]
	v_mul_f32_e32 v40, v43, v40
	v_cndmask_b32_e64 v16, v16, 0, s[46:47]
	v_cndmask_b32_e64 v40, v40, 0, s[52:53]
	v_cvt_pk_bf16_f32 v18, v16, v18
	v_cvt_pk_bf16_f32 v19, v19, v40
	ds_write_b64 v83, v[18:19]
	ds_read_b128 v[40:43], v82 offset:64
	s_waitcnt lgkmcnt(0)
	v_sub_f32_e32 v16, v123, v40
	v_mul_f32_e32 v16, 0x3fb8aa3b, v16
	v_sub_f32_e32 v18, v123, v41
	v_exp_f32_e32 v16, v16
	v_mul_f32_e32 v18, 0x3fb8aa3b, v18
	v_exp_f32_e32 v18, v18
	v_sub_f32_e32 v19, v123, v42
	v_mul_f32_e32 v16, v36, v16
	v_sub_f32_e32 v36, v123, v43
	v_mul_f32_e32 v18, v37, v18
	v_mul_f32_e32 v19, 0x3fb8aa3b, v19
	v_mul_f32_e32 v36, 0x3fb8aa3b, v36
	v_cndmask_b32_e64 v16, v16, 0, s[54:55]
	v_cndmask_b32_e64 v18, 0, v18, s[56:57]
	v_exp_f32_e32 v19, v19
	v_exp_f32_e32 v36, v36
	v_cvt_pk_bf16_f32 v18, v16, v18
	v_mul_f32_e32 v16, 0x3fb8aa3b, v123
	v_exp_f32_e32 v16, v16
	v_mul_f32_e32 v19, v38, v19
	v_mul_f32_e32 v36, v39, v36
	v_cndmask_b32_e64 v19, v19, 0, s[58:59]
	v_cndmask_b32_e64 v36, v36, 0, s[60:61]
	v_cvt_pk_bf16_f32 v19, v19, v36
	ds_write_b64 v83, v[18:19] offset:32
	v_pk_mul_f32 v[36:37], v[16:17], v[44:45] op_sel_hi:[0,1]
	v_pk_mul_f32 v[38:39], v[16:17], v[46:47] op_sel_hi:[0,1]
	v_pk_mul_f32 v[40:41], v[16:17], v[48:49] op_sel_hi:[0,1]
	v_pk_mul_f32 v[42:43], v[16:17], v[50:51] op_sel_hi:[0,1]
	s_waitcnt lgkmcnt(0)
	s_barrier
; __device__ __forceinline__ unsigned cvt_pk_bf16(float lo, float hi) { unsigned r; asm("v_cvt_pk_bf16_f32 %0, %1, %2" : "=v"(r) : "v"(lo), "v"(hi)); return r; }
; template <int DK, int DV, bool SEPQ> ...
;     ...
; #pragma unroll
;     for (int ks = 0; ks < 2; ++ks) { const bf16x8 pf = *(const bf16x8*)(P + (16 * m + fr) * LJ + 32 * ks + 8 * fq);
; #pragma unroll
;         for (int vt = 0; vt < NVTW; ++vt) { const bf16x8 vf = *(const bf16x8*)(VT + (16 * (hw * NVTW + vt) + fr) * LJ + 32 * ks + 8 * fq); O[vt] = __builtin_amdgcn_mfma_f32_16x16x32_bf16(vf, pf, O[vt], 0, 0, 0); } }
; #pragma unroll
;     for (int ct = 0; ct < NCTW; ++ct) { const int ctg = wid * NCTW + ct; const f32x4 dec = *(const f32x4*)(SDEC + 16 * ctg + 4 * fq);
; #pragma unroll
;         for (int vt = 0; vt < NVT; ++vt) S[ct][vt] = S[ct][vt] * dec;
; #pragma unroll
;         for (int ks = 0; ks < 2; ++ks) { const bf16x8 kf = *(const bf16x8*)(KT + (16 * ctg + fr) * LJ + 32 * ks + 8 * fq);
; #pragma unroll
;             for (int vt = 0; vt < NVT; ++vt) { const bf16x8 vf = *(const bf16x8*)(VT2 + (16 * vt + fr) * LJ + 32 * ks + 8 * fq); S[ct][vt] = __builtin_amdgcn_mfma_f32_16x16x32_bf16(kf, vf, S[ct][vt], 0, 0, 0); } } }
; __device__ __forceinline__ void mamba_block(ArgsP a_, unsigned char* smem) { const ArgsP a = a_;
;     ...
;         const int m = wid >> 1, hw = wid & 1, i = 16 * m + fr;
;         if (i < len) { const float Dh = AIN(24)[hd];
; #pragma unroll
;             for (int vt = 0; vt < 2; ++vt) { const int v = 16 * (hw * 2 + vt) + 4 * fq; const size_t o = (size_t)(row0 + i) * 2048 + hd * 64 + v;
;                 const u32x2 xt = *(const u32x2*)(XC + (size_t)(row0 + i) * 4096 + hd * 64 + v); const u32x2 zt = *(const u32x2*)(ZG + o);
;                 const f32x4 xs = {__uint_as_float(xt.x << 16), __uint_as_float(xt.x & 0xffff0000u), __uint_as_float(xt.y << 16), __uint_as_float(xt.y & 0xffff0000u)};
;                 const f32x4 zg = {__uint_as_float(zt.x << 16), __uint_as_float(zt.x & 0xffff0000u), __uint_as_float(zt.y << 16), __uint_as_float(zt.y & 0xffff0000u)};
;                 const f32x4 y = (O[vt] + xs * Dh) * zg; *(u32x2*)(YB + o) = (u32x2){cvt_pk_bf16(y[0], y[1]), cvt_pk_bf16(y[2], y[3])}; } }
	ds_read_b128 v[220:223], v84
	ds_read_b128 v[224:227], v110 offset:53248
	ds_read_b128 v[228:231], v110 offset:55552
	ds_read_b128 v[232:235], v84 offset:64
	ds_read_b128 v[236:239], v110 offset:53312
	ds_read_b128 v[240:243], v110 offset:55616
	ds_read_b128 v[244:247], v111
	ds_read_b128 v[248:251], v70 offset:34816
	ds_read_b128 v[164:167], v112 offset:62464
	ds_read_b128 v[168:171], v112 offset:64768
	ds_read_b128 v[172:175], v113 offset:62464
	ds_read_b128 v[176:179], v113 offset:64768
	ds_read_b128 v[180:183], v70 offset:34880
	s_waitcnt lgkmcnt(11)
	v_mfma_f32_16x16x32_bf16 v[36:39], v[224:227], v[220:223], v[36:39]
	ds_read_b128 v[224:227], v112 offset:62528
	s_waitcnt lgkmcnt(11)
	v_mfma_f32_16x16x32_bf16 v[44:47], v[228:231], v[220:223], v[40:43]
	ds_read_b128 v[220:223], v112 offset:64832
	ds_read_b128 v[228:231], v113 offset:62528
	s_nop 1
	s_waitcnt lgkmcnt(11)
	v_mfma_f32_16x16x32_bf16 v[40:43], v[236:239], v[232:235], v[36:39]
	ds_read_b128 v[236:239], v113 offset:64832
	s_nop 2
	s_waitcnt lgkmcnt(11)
	v_mfma_f32_16x16x32_bf16 v[36:39], v[240:243], v[232:235], v[44:47]
	s_nop 2
	s_waitcnt lgkmcnt(10)
	v_pk_mul_f32 v[22:23], v[22:23], v[246:247]
	v_pk_mul_f32 v[20:21], v[20:21], v[244:245]
	v_pk_mul_f32 v[24:25], v[24:25], v[244:245]
	v_pk_mul_f32 v[26:27], v[26:27], v[246:247]
	v_pk_mul_f32 v[28:29], v[28:29], v[244:245]
	v_pk_mul_f32 v[30:31], v[30:31], v[246:247]
	v_pk_mul_f32 v[32:33], v[32:33], v[244:245]
	v_pk_mul_f32 v[34:35], v[34:35], v[246:247]
	s_waitcnt lgkmcnt(8)
	v_mfma_f32_16x16x32_bf16 v[18:21], v[248:251], v[164:167], v[20:23]
	s_waitcnt lgkmcnt(7)
	v_mfma_f32_16x16x32_bf16 v[24:27], v[248:251], v[168:171], v[24:27]
	s_waitcnt lgkmcnt(6)
	v_mfma_f32_16x16x32_bf16 v[28:31], v[248:251], v[172:175], v[28:31]
	s_waitcnt lgkmcnt(5)
	v_mfma_f32_16x16x32_bf16 v[32:35], v[248:251], v[176:179], v[32:35]
	s_waitcnt lgkmcnt(3)
	v_mfma_f32_16x16x32_bf16 v[20:23], v[180:183], v[224:227], v[18:21]
	s_waitcnt lgkmcnt(2)
	v_mfma_f32_16x16x32_bf16 v[24:27], v[180:183], v[220:223], v[24:27]
	s_waitcnt lgkmcnt(1)
	v_mfma_f32_16x16x32_bf16 v[28:31], v[180:183], v[228:231], v[28:31]
	s_waitcnt lgkmcnt(0)
	v_mfma_f32_16x16x32_bf16 v[32:35], v[180:183], v[236:239], v[32:35]
	s_and_saveexec_b64 s[74:75], vcc
	s_cbranch_execz .LBB0_374
	v_add_u32_e32 v44, s72, v71
	v_ashrrev_i32_e32 v45, 31, v44
	s_waitcnt vmcnt(0)
	v_mov_b32_e32 v18, v210
	v_readlane_b32 s22, v255, 12
	v_lshlrev_b64 v[46:47], 11, v[44:45]
	v_lshlrev_b64 v[44:45], 13, v[44:45]
	v_readlane_b32 s23, v255, 13
	v_lshl_or_b32 v19, s71, 6, v46
	v_or_b32_e32 v46, v19, v66
	v_lshl_add_u64 v[44:45], s[22:23], 0, v[44:45]
	s_lshl_b32 s22, s71, 7
	s_mov_b32 s23, s12
	v_lshl_add_u64 v[44:45], v[44:45], 0, s[22:23]
	v_lshlrev_b32_e32 v16, 1, v66
	v_lshl_add_u64 v[44:45], v[44:45], 0, v[16:17]
	v_lshlrev_b64 v[50:51], 1, v[46:47]
	v_mov_b32_e32 v48, v202
	v_mov_b32_e32 v49, v203
	v_lshl_add_u64 v[52:53], s[24:25], 0, v[50:51]
	v_mov_b32_e32 v52, v204
	v_mov_b32_e32 v53, v205
	v_or_b32_e32 v46, v19, v68
	v_lshlrev_b32_e32 v54, 16, v48
	v_and_b32_e32 v55, 0xffff0000, v48
	v_lshlrev_b32_e32 v48, 16, v49
	v_and_b32_e32 v49, 0xffff0000, v49
	v_lshlrev_b32_e32 v124, 16, v52
	v_and_b32_e32 v125, 0xffff0000, v52
	v_lshlrev_b32_e32 v52, 16, v53
	v_and_b32_e32 v53, 0xffff0000, v53
	v_pk_fma_f32 v[40:41], v[18:19], v[54:55], v[40:41] op_sel_hi:[0,1,1]
	v_pk_fma_f32 v[42:43], v[18:19], v[48:49], v[42:43] op_sel_hi:[0,1,1]
	v_pk_mul_f32 v[42:43], v[42:43], v[52:53]
	v_pk_mul_f32 v[40:41], v[40:41], v[124:125]
	s_nop 0
	v_cvt_pk_bf16_f32 v40, v40, v41
	v_cvt_pk_bf16_f32 v41, v42, v43
	v_lshl_add_u64 v[42:43], s[26:27], 0, v[50:51]
	global_store_dwordx2 v[42:43], v[40:41], off
	v_lshlrev_b64 v[42:43], 1, v[46:47]
	v_mov_b32_e32 v40, v206
	v_mov_b32_e32 v41, v207
	v_lshl_add_u64 v[44:45], s[24:25], 0, v[42:43]
	v_mov_b32_e32 v44, v208
	v_mov_b32_e32 v45, v209
	v_lshlrev_b32_e32 v46, 16, v40
	v_and_b32_e32 v47, 0xffff0000, v40
	v_lshlrev_b32_e32 v40, 16, v41
	v_and_b32_e32 v41, 0xffff0000, v41
	v_lshlrev_b32_e32 v48, 16, v44
	v_and_b32_e32 v49, 0xffff0000, v44
	v_lshlrev_b32_e32 v44, 16, v45
	v_and_b32_e32 v45, 0xffff0000, v45
	v_pk_fma_f32 v[36:37], v[18:19], v[46:47], v[36:37] op_sel_hi:[0,1,1]
	v_pk_fma_f32 v[18:19], v[18:19], v[40:41], v[38:39] op_sel_hi:[0,1,1]
	v_pk_mul_f32 v[18:19], v[18:19], v[44:45]
	v_pk_mul_f32 v[36:37], v[36:37], v[48:49]
	s_nop 0
	v_cvt_pk_bf16_f32 v36, v36, v37
	v_cvt_pk_bf16_f32 v37, v18, v19
	v_lshl_add_u64 v[18:19], s[26:27], 0, v[42:43]
	global_store_dwordx2 v[18:19], v[36:37], off
